# v33: rstd table fills of P1/P3/P9 restructured to one unit ordinal per wave (unit-decode arithmetic runs once instead of 4x; loads and summation order unchanged)
# speedup vs baseline: 1.0007x; 1.0007x over previous
;     __device__ __forceinline__ bool next(int i, Unit& u) const {
;         const long L = (long)(i >> psh) * G + c; if (L >= nwg) return false;
;         int wgid = (int)L; { const int q = nwg / NXCD, r = nwg % NXCD, xcd = wgid % NXCD, off = wgid / NXCD; wgid = (xcd < r ? xcd * (q + 1) : r * (q + 1) + (xcd - r) * q) + off; }
;         const int nig = WGM * nN, gid = wgid / nig, fm = gid * WGM, gsz = (nM - fm) < WGM ? (nM - fm) : WGM;
;         u.pm = fm + ((wgid % nig) % gsz); u.pn = (wgid % nig) / gsz; u.part = i & ((1 << psh) - 1); u.idx = i; return true;
;     }
; __global__ void __launch_bounds__(NTHREADS, 2) fwd_kernel(Params P) {
;     ...
;     if (IN(1)) {
;         pg8::Gemm g{XA, Wup1, D, D, D, 0}; pg8::Sched S; S.init(M, NUP, G, bx, 0);
;         RSTD_TABLE_FILL(S, ssq0, true);
.LBB0_312:
	s_cmp_lt_i32 s94, 2
	s_cselect_b64 s[4:5], -1, 0
	s_add_u32 s88, s68, 0x580000
	s_addc_u32 s89, s69, 0
	s_add_u32 s80, s68, 0x4680000
	s_addc_u32 s81, s69, 0
	s_and_b64 s[10:11], s[4:5], s[0:1]
	s_andn2_b64 vcc, exec, s[10:11]
	v_lshrrev_b32_e32 v199, 8, v0
	v_writelane_b32 v252, s88, 16
	s_nop 1
	v_writelane_b32 v252, s89, 17
	s_cbranch_vccnz .LBB0_591
	s_ashr_i32 s3, s2, 31
	s_waitcnt vmcnt(15)
	v_lshrrev_b32_e32 v254, 6, v0
	v_mov_b64_e32 v[2:3], s[2:3]
	v_mad_i64_i32 v[2:3], s[0:1], v254, s71, v[2:3]
	s_mov_b64 s[0:1], 0x596
	s_ashr_i32 s33, s71, 31
	v_cmp_gt_i64_e32 vcc, s[0:1], v[2:3]
	v_mov_b32_e32 v3, 0
	s_and_saveexec_b64 s[4:5], vcc
	s_cbranch_execz .LBB0_319
	v_ashrrev_i32_e32 v3, 31, v2
	v_lshrrev_b32_e32 v3, 29, v3
	v_add_u32_e32 v4, v2, v3
	v_and_b32_e32 v3, -8, v4
	v_sub_u32_e32 v3, v2, v3
	v_cmp_lt_i32_e64 s[0:1], 5, v3
	s_and_saveexec_b64 s[6:7], s[0:1]
	s_xor_b64 s[0:1], exec, s[6:7]
	s_movk_i32 s6, 0xb2
	v_mad_u64_u32 v[2:3], s[6:7], v3, s6, 6
	s_or_saveexec_b64 s[0:1], s[0:1]
	v_ashrrev_i32_e32 v4, 3, v4
	s_xor_b64 exec, exec, s[0:1]
	s_movk_i32 s6, 0xb3
	v_mul_lo_u32 v2, v3, s6
	s_or_b64 exec, exec, s[0:1]
	v_add_u32_e32 v2, v2, v4
	s_mov_b32 s0, 0x2e8ba2e9
	v_mul_hi_i32 v3, v2, s0
	v_lshrrev_b32_e32 v4, 31, v3
	v_ashrrev_i32_e32 v3, 4, v3
	v_add_u32_e32 v3, v3, v4
	v_lshlrev_b32_e32 v4, 2, v3
	v_sub_u32_e32 v5, 0x41, v4
	v_min_i32_e32 v5, 4, v5
	s_waitcnt vmcnt(14)
	v_sub_u32_e32 v6, 0, v5
	v_max_i32_e32 v5, v5, v6
	v_cvt_f32_u32_e32 v6, v5
	s_movk_i32 s0, 0x58
	v_mul_lo_u32 v3, v3, s0
	v_sub_u32_e32 v2, v2, v3
	v_rcp_iflag_f32_e32 v6, v6
	v_sub_u32_e32 v7, 0, v2
	v_ashrrev_i32_e32 v3, 31, v2
	v_max_i32_e32 v2, v2, v7
	v_mul_f32_e32 v6, 0x4f7ffffe, v6
	v_cvt_u32_f32_e32 v6, v6
	v_sub_u32_e32 v7, 0, v5
	v_mul_lo_u32 v7, v7, v6
	v_mul_hi_u32 v7, v6, v7
	v_add_u32_e32 v6, v6, v7
	v_mul_hi_u32 v6, v2, v6
	v_mul_lo_u32 v6, v6, v5
	v_sub_u32_e32 v2, v2, v6
	v_sub_u32_e32 v6, v2, v5
	v_cmp_ge_u32_e64 s[0:1], v2, v5
	s_nop 1
	v_cndmask_b32_e64 v2, v2, v6, s[0:1]
	v_sub_u32_e32 v6, v2, v5
	v_cmp_ge_u32_e64 s[0:1], v2, v5
	s_nop 1
	v_cndmask_b32_e64 v2, v2, v6, s[0:1]
	v_xor_b32_e32 v2, v2, v3
	v_sub_u32_e32 v2, v2, v3
	v_add_lshl_u32 v3, v4, v2, 8
.LBB0_319:
	s_or_b64 exec, exec, s[4:5]
	v_and_b32_e32 v4, 63, v0
	v_or_b32_e32 v2, v3, v4
	s_add_u32 s18, s68, 0x10000
	v_ashrrev_i32_e32 v3, 31, v2
	s_addc_u32 s19, s69, 0
	v_lshlrev_b64 v[2:3], 6, v[2:3]
	v_lshl_add_u64 v[2:3], s[18:19], 0, v[2:3]
	s_mov_b64 s[0:1], 0x1000
	global_load_dword v240, v[2:3], off
	v_lshl_add_u64 v[6:7], v[2:3], 0, s[0:1]
	global_load_dword v241, v[6:7], off
	v_lshl_add_u64 v[8:9], v[6:7], 0, s[0:1]
	global_load_dword v242, v[8:9], off
	v_lshl_add_u64 v[6:7], v[8:9], 0, s[0:1]
	global_load_dword v243, v[6:7], off
	v_lshlrev_b32_e32 v3, 10, v254
	v_lshl_add_u32 v3, v4, 2, v3
	v_add_u32_e32 v3, 0x20800, v3
	s_waitcnt vmcnt(0)
	ds_write_b32 v3, v240
	ds_write_b32 v3, v241 offset:256
	ds_write_b32 v3, v242 offset:512
	ds_write_b32 v3, v243 offset:768
.LBB0_342:
	v_readlane_b32 s0, v252, 12
	v_readlane_b32 s1, v252, 13
	s_andn2_b64 vcc, exec, s[0:1]
	s_waitcnt lgkmcnt(0)
	s_barrier
	s_cbranch_vccnz .LBB0_567
	s_abs_i32 s0, s71
	v_cvt_f32_u32_e32 v2, s0
	s_sub_i32 s1, 0, s0
	v_rcp_iflag_f32_e32 v2, v2
	s_nop 0
	v_mul_f32_e32 v2, 0x4f7ffffe, v2
	v_cvt_u32_f32_e32 v2, v2
	s_nop 0
	v_readfirstlane_b32 s4, v2
	s_mul_i32 s1, s1, s4
	s_mul_hi_u32 s1, s4, s1
	s_add_i32 s4, s4, s1
	s_mul_hi_u32 s1, s4, 0x596
	s_mul_i32 s1, s1, s0
	s_sub_i32 s1, 0x596, s1
	s_sub_i32 s4, s1, s0
	s_cmp_ge_u32 s1, s0
	s_cselect_b32 s1, s4, s1
	s_sub_i32 s4, s1, s0
	s_cmp_ge_u32 s1, s0
	s_cselect_b32 s20, s4, s1
	s_sub_i32 s0, s2, s20
	s_cmp_lt_i32 s0, 0
	s_cbranch_scc1 .LBB0_566
	s_lshl_b32 s0, s0, 3
	v_readlane_b32 s1, v252, 11
	s_add_i32 s24, s0, s1
	s_cmpk_gt_i32 s24, 0x18ff
	s_cbranch_scc1 .LBB0_566
	s_cmpk_gt_i32 s24, 0x57f
	s_cbranch_scc0 .LBB0_352
	s_cmpk_gt_u32 s24, 0x12ff
	s_mov_b64 s[8:9], -1
	s_cbranch_scc0 .LBB0_353
	s_cmpk_gt_u32 s24, 0x16ff
	s_cbranch_scc0 .LBB0_354
	s_add_i32 s0, s24, 0xffffe900
	s_lshr_b32 s21, s0, 5
	s_mov_b64 s[4:5], 0
	s_mov_b64 s[0:1], s[40:41]
	s_branch .LBB0_355

; __global__ void __launch_bounds__(NTHREADS, 2) fwd_kernel(Params P) {
;     ...
;     if (IN(3)) {
;         pg8::Gemm g{XA, Win, D, D, D, 0}; pg8::Sched S; S.init(M, NIN_V, G, bx, 0);
;         RSTD_TABLE_FILL(S, ssq1, false);
;         pg8::EpiIn E{QK, Vb, Gb, AB, SKV, GA, rtab, P.in[13], P.in[14], out};
.LBB0_760:
	v_writelane_b32 v252, s91, 25
	v_writelane_b32 v252, s92, 26
	s_nop 1
	v_writelane_b32 v252, s93, 27
	v_writelane_b32 v252, s94, 28
	s_cmp_lt_i32 s94, 4
	s_cselect_b64 s[4:5], -1, 0
	s_add_u32 s96, s68, 0x420000
	s_addc_u32 s97, s69, 0
	s_add_u32 s40, s68, 0x2600000
	s_addc_u32 s41, s69, 0
	v_writelane_b32 v252, s95, 29
	s_add_u32 s94, s68, 0x6700000
	s_addc_u32 s95, s69, 0
	s_add_u32 s92, s68, 0xa800000
	s_addc_u32 s93, s69, 0
	s_add_u32 s74, s68, 0xe900000
	s_addc_u32 s75, s69, 0
	s_and_b64 s[38:39], s[4:5], s[0:1]
	s_andn2_b64 vcc, exec, s[38:39]
	s_cbranch_vccnz .LBB0_988
	s_ashr_i32 s3, s2, 31
	s_waitcnt vmcnt(0) lgkmcnt(0)
	v_lshrrev_b32_e32 v254, 6, v0
	v_mov_b64_e32 v[2:3], s[2:3]
	v_mad_i64_i32 v[2:3], s[0:1], v254, s71, v[2:3]
	s_mov_b64 s[0:1], 0x6db
	s_ashr_i32 s33, s71, 31
	v_cmp_gt_i64_e32 vcc, s[0:1], v[2:3]
	v_mov_b32_e32 v3, 0
	s_and_saveexec_b64 s[4:5], vcc
	s_cbranch_execz .LBB0_767
	v_ashrrev_i32_e32 v3, 31, v2
	v_lshrrev_b32_e32 v3, 29, v3
	v_add_u32_e32 v4, v2, v3
	v_and_b32_e32 v3, -8, v4
	v_sub_u32_e32 v3, v2, v3
	v_cmp_lt_i32_e64 s[0:1], 2, v3
	s_and_saveexec_b64 s[6:7], s[0:1]
	s_xor_b64 s[0:1], exec, s[6:7]
	s_movk_i32 s6, 0xdb
	v_mad_u64_u32 v[2:3], s[6:7], v3, s6, 3
	s_or_saveexec_b64 s[0:1], s[0:1]
	v_ashrrev_i32_e32 v4, 3, v4
	s_xor_b64 exec, exec, s[0:1]
	s_movk_i32 s6, 0xdc
	v_mul_lo_u32 v2, v3, s6
	s_or_b64 exec, exec, s[0:1]
	v_add_u32_e32 v2, v2, v4
	s_mov_b32 s0, 0x4bda12f7
	v_mul_hi_i32 v3, v2, s0
	v_lshrrev_b32_e32 v4, 31, v3
	v_ashrrev_i32_e32 v3, 5, v3
	v_add_u32_e32 v3, v3, v4
	v_lshlrev_b32_e32 v4, 2, v3
	v_sub_u32_e32 v5, 0x41, v4
	v_min_i32_e32 v5, 4, v5
	v_sub_u32_e32 v6, 0, v5
	v_max_i32_e32 v5, v5, v6
	v_cvt_f32_u32_e32 v6, v5
	s_movk_i32 s0, 0x6c
	v_mul_lo_u32 v3, v3, s0
	v_sub_u32_e32 v2, v2, v3
	v_rcp_iflag_f32_e32 v6, v6
	v_sub_u32_e32 v7, 0, v2
	v_ashrrev_i32_e32 v3, 31, v2
	v_max_i32_e32 v2, v2, v7
	v_mul_f32_e32 v6, 0x4f7ffffe, v6
	v_cvt_u32_f32_e32 v6, v6
	v_sub_u32_e32 v7, 0, v5
	v_mul_lo_u32 v7, v7, v6
	v_mul_hi_u32 v7, v6, v7
	v_add_u32_e32 v6, v6, v7
	v_mul_hi_u32 v6, v2, v6
	v_mul_lo_u32 v6, v6, v5
	v_sub_u32_e32 v2, v2, v6
	v_sub_u32_e32 v6, v2, v5
	v_cmp_ge_u32_e64 s[0:1], v2, v5
	s_nop 1
	v_cndmask_b32_e64 v2, v2, v6, s[0:1]
	v_sub_u32_e32 v6, v2, v5
	v_cmp_ge_u32_e64 s[0:1], v2, v5
	s_nop 1
	v_cndmask_b32_e64 v2, v2, v6, s[0:1]
	v_xor_b32_e32 v2, v2, v3
	v_sub_u32_e32 v2, v2, v3
	v_add_lshl_u32 v3, v4, v2, 8
.LBB0_767:
	s_or_b64 exec, exec, s[4:5]
	v_and_b32_e32 v4, 63, v0
	v_or_b32_e32 v2, v3, v4
	v_ashrrev_i32_e32 v3, 31, v2
	v_lshlrev_b64 v[2:3], 6, v[2:3]
	v_lshl_add_u64 v[14:15], s[22:23], 0, v[2:3]
	s_mov_b64 s[0:1], 0x1000
	v_lshl_add_u64 v[30:31], v[14:15], 0, s[0:1]
	v_lshl_add_u64 v[46:47], v[30:31], 0, s[0:1]
	v_lshl_add_u64 v[62:63], v[46:47], 0, s[0:1]
	v_lshlrev_b32_e32 v66, 10, v254
	v_lshl_add_u32 v66, v4, 2, v66
	v_add_u32_e32 v66, 0x20800, v66
	global_load_dwordx4 v[2:5], v[14:15], off offset:48
	global_load_dwordx4 v[6:9], v[14:15], off offset:32
	global_load_dwordx4 v[10:13], v[14:15], off offset:16
	s_nop 0
	global_load_dwordx4 v[14:17], v[14:15], off
	global_load_dwordx4 v[18:21], v[30:31], off offset:48
	global_load_dwordx4 v[22:25], v[30:31], off offset:32
	global_load_dwordx4 v[26:29], v[30:31], off offset:16
	s_nop 0
	global_load_dwordx4 v[30:33], v[30:31], off
	global_load_dwordx4 v[34:37], v[46:47], off offset:48
	global_load_dwordx4 v[38:41], v[46:47], off offset:32
	global_load_dwordx4 v[42:45], v[46:47], off offset:16
	s_nop 0
	global_load_dwordx4 v[46:49], v[46:47], off
	global_load_dwordx4 v[50:53], v[62:63], off offset:48
	global_load_dwordx4 v[54:57], v[62:63], off offset:32
	global_load_dwordx4 v[58:61], v[62:63], off offset:16
	s_nop 0
	global_load_dwordx4 v[62:65], v[62:63], off
	s_waitcnt vmcnt(12)
	v_mov_b32_e32 v68, v15
	v_mov_b32_e32 v69, v16
	v_mov_b32_e32 v15, v17
	v_mov_b32_e32 v16, v11
	v_mov_b32_e32 v17, v12
	v_mov_b32_e32 v11, v13
	v_pk_add_f32 v[14:15], v[68:69], v[14:15]
	v_pk_add_f32 v[10:11], v[16:17], v[10:11]
	v_pk_add_f32 v[14:15], v[14:15], v[14:15] op_sel:[0,1] op_sel_hi:[1,0]
	v_pk_add_f32 v[10:11], v[10:11], v[10:11] op_sel:[0,1] op_sel_hi:[1,0]
	v_add_f32_e32 v6, v6, v7
	v_add_f32_e32 v8, v8, v9
	v_mov_b32_e32 v15, v2
	v_mov_b32_e32 v11, v3
	v_mov_b32_e32 v7, v4
	v_mov_b32_e32 v9, v5
	v_pk_add_f32 v[2:3], v[14:15], v[10:11]
	v_pk_add_f32 v[4:5], v[6:7], v[8:9]
	s_nop 0
	v_pk_add_f32 v[2:3], v[2:3], v[4:5]
	s_nop 0
	v_add_f32_e32 v2, v2, v3
	v_mov_b32_e32 v3, 0x358637bd
	v_fmac_f32_e32 v3, 0x3a800000, v2
	v_rsq_f32_e32 v2, v3
	ds_write_b32 v66, v2
	s_waitcnt vmcnt(8)
	v_mov_b32_e32 v2, v31
	v_mov_b32_e32 v3, v32
	v_mov_b32_e32 v31, v33
	v_mov_b32_e32 v4, v27
	v_mov_b32_e32 v5, v28
	v_mov_b32_e32 v27, v29
	v_pk_add_f32 v[2:3], v[2:3], v[30:31]
	v_pk_add_f32 v[4:5], v[4:5], v[26:27]
	v_pk_add_f32 v[2:3], v[2:3], v[2:3] op_sel:[0,1] op_sel_hi:[1,0]
	v_pk_add_f32 v[4:5], v[4:5], v[4:5] op_sel:[0,1] op_sel_hi:[1,0]
	v_add_f32_e32 v6, v22, v23
	v_add_f32_e32 v8, v24, v25
	v_mov_b32_e32 v3, v18
	v_mov_b32_e32 v5, v19
	v_mov_b32_e32 v7, v20
	v_mov_b32_e32 v9, v21
	v_pk_add_f32 v[2:3], v[2:3], v[4:5]
	v_pk_add_f32 v[4:5], v[6:7], v[8:9]
	s_nop 0
	v_pk_add_f32 v[2:3], v[2:3], v[4:5]
	s_nop 0
	v_add_f32_e32 v2, v2, v3
	v_mov_b32_e32 v3, 0x358637bd
	v_fmac_f32_e32 v3, 0x3a800000, v2
	v_rsq_f32_e32 v2, v3
	ds_write_b32 v66, v2 offset:256
	s_waitcnt vmcnt(4)
	v_mov_b32_e32 v2, v47
	v_mov_b32_e32 v3, v48
	v_mov_b32_e32 v47, v49
	v_mov_b32_e32 v4, v43
	v_mov_b32_e32 v5, v44
	v_mov_b32_e32 v43, v45
	v_pk_add_f32 v[2:3], v[2:3], v[46:47]
	v_pk_add_f32 v[4:5], v[4:5], v[42:43]
	v_pk_add_f32 v[2:3], v[2:3], v[2:3] op_sel:[0,1] op_sel_hi:[1,0]
	v_pk_add_f32 v[4:5], v[4:5], v[4:5] op_sel:[0,1] op_sel_hi:[1,0]
	v_add_f32_e32 v6, v38, v39
	v_add_f32_e32 v8, v40, v41
	v_mov_b32_e32 v3, v34
	v_mov_b32_e32 v5, v35
	v_mov_b32_e32 v7, v36
	v_mov_b32_e32 v9, v37
	v_pk_add_f32 v[2:3], v[2:3], v[4:5]
	v_pk_add_f32 v[4:5], v[6:7], v[8:9]
	s_nop 0
	v_pk_add_f32 v[2:3], v[2:3], v[4:5]
	s_nop 0
	v_add_f32_e32 v2, v2, v3
	v_mov_b32_e32 v3, 0x358637bd
	v_fmac_f32_e32 v3, 0x3a800000, v2
	v_rsq_f32_e32 v2, v3
	ds_write_b32 v66, v2 offset:512
	s_waitcnt vmcnt(0)
	v_mov_b32_e32 v2, v63
	v_mov_b32_e32 v3, v64
	v_mov_b32_e32 v63, v65
	v_mov_b32_e32 v4, v59
	v_mov_b32_e32 v5, v60
	v_mov_b32_e32 v59, v61
	v_pk_add_f32 v[2:3], v[2:3], v[62:63]
	v_pk_add_f32 v[4:5], v[4:5], v[58:59]
	v_pk_add_f32 v[2:3], v[2:3], v[2:3] op_sel:[0,1] op_sel_hi:[1,0]
	v_pk_add_f32 v[4:5], v[4:5], v[4:5] op_sel:[0,1] op_sel_hi:[1,0]
	v_add_f32_e32 v6, v54, v55
	v_add_f32_e32 v8, v56, v57
	v_mov_b32_e32 v3, v50
	v_mov_b32_e32 v5, v51
	v_mov_b32_e32 v7, v52
	v_mov_b32_e32 v9, v53
	v_pk_add_f32 v[2:3], v[2:3], v[4:5]
	v_pk_add_f32 v[4:5], v[6:7], v[8:9]
	s_nop 0
	v_pk_add_f32 v[2:3], v[2:3], v[4:5]
	s_nop 0
	v_add_f32_e32 v2, v2, v3
	v_mov_b32_e32 v3, 0x358637bd
	v_fmac_f32_e32 v3, 0x3a800000, v2
	v_rsq_f32_e32 v2, v3
	ds_write_b32 v66, v2 offset:768
; #define LAS __attribute__((address_space(3)))
; #define CONV_LANDED(s_) do { asm volatile("" :: "v"((s_).v[0]), "v"((s_).v[1]), "v"((s_).v[2]), "v"((s_).v[3]), "v"((s_).v[4]), "v"((s_).v[5]), "v"((s_).v[6]), "v"((s_).v[7]), "v"((s_).g0), "v"((s_).g1)); } while (0)
; #define CONV_JOB(it_) conv_job<LIST>((it_) < n ? (it_) : n - 1, P)
; #define CONVERT_ON_LIGHT(LIST, nwg_) do { const int rem_ = (nwg_) % G; const int nl_ = rem_ ? G - rem_ : G, lc_ = rem_ ? bx - rem_ : bx; \
;         if (lc_ >= 0) CONVERT_LIST(LIST, lc_ * NWAVES + wave, nl_ * NWAVES); } while (0)
; template <int LIST> __device__ __forceinline__ void convert_list(int first, int stride, const Params& P, LAS float* scr, int lane) {
;     constexpr int n = conv_count<LIST>();
;     if (first >= n) return;
;     ConvSet A, B, C;
;     ...
;     conv_fetch(CONV_JOB(first), lane, A); conv_fetch(CONV_JOB(first + stride), lane, B);
;     CONV_LANDED(A); CONV_LANDED(B);
; __global__ void __launch_bounds__(NTHREADS, 2) fwd_kernel(Params P) {
;     ...
;         RSTD_TABLE_FILL(S, ssq1, false);
;         pg8::EpiIn E{QK, Vb, Gb, AB, SKV, GA, rtab, P.in[13], P.in[14], out};
;         if (split_conv) { CONVERT_ON_LIGHT(2, (M / 256) * (NIN_V / 256)); __syncthreads(); }
.LBB0_790:
	v_readlane_b32 s0, v252, 12
	v_readlane_b32 s1, v252, 13
	s_andn2_b64 vcc, exec, s[0:1]
	s_waitcnt lgkmcnt(0)
	s_barrier
	s_cbranch_vccnz .LBB0_803
	s_abs_i32 s0, s71
	s_waitcnt vmcnt(15)
	v_cvt_f32_u32_e32 v2, s0
	s_sub_i32 s1, 0, s0
	v_rcp_iflag_f32_e32 v2, v2
	s_nop 0
	v_mul_f32_e32 v2, 0x4f7ffffe, v2
	v_cvt_u32_f32_e32 v2, v2
	s_nop 0
	v_readfirstlane_b32 s4, v2
	s_mul_i32 s1, s1, s4
	s_mul_hi_u32 s1, s4, s1
	s_add_i32 s4, s4, s1
	s_mul_hi_u32 s1, s4, 0x6db
	s_mul_i32 s1, s1, s0
	s_sub_i32 s1, 0x6db, s1
	s_sub_i32 s4, s1, s0
	s_cmp_ge_u32 s1, s0
	s_cselect_b32 s1, s4, s1
	s_sub_i32 s4, s1, s0
	s_cmp_ge_u32 s1, s0
	s_cselect_b32 s4, s4, s1
	s_sub_i32 s0, s2, s4
	s_cmp_lt_i32 s0, 0
	s_cbranch_scc1 .LBB0_802
	s_lshl_b32 s8, s0, 3
	v_readlane_b32 s0, v252, 11
	s_add_i32 s6, s8, s0
	s_cmpk_gt_i32 s6, 0xaff
	s_cbranch_scc1 .LBB0_802
	v_readlane_b32 s28, v252, 11
	s_lshl_b32 s0, s28, 14
	s_add_i32 s5, s0, 0
	s_mul_hi_u32 s0, s6, 0xba2e8ba3
	s_lshr_b32 s0, s0, 7
	s_mul_i32 s1, s0, 0xb0
	s_sub_i32 s1, s6, s1
	s_lshl_b32 s10, s0, 6
	s_bfe_i32 s0, s1, 0x10002
	s_lshl_b32 s9, s1, 4
	s_and_b32 s0, s0, 0xb00
	s_and_b32 s9, s9, 0xf80
	s_lshl_b32 s1, s1, 5
	s_sub_i32 s23, s71, s4
	s_add_i32 s0, s0, s9
	s_and_b32 s1, s1, 0x60
	s_lshl_b32 s7, s23, 3
	s_or_b32 s20, s0, s1
	s_mov_b32 s11, 0
	s_cmp_eq_u64 s[42:43], 0
	s_cselect_b64 s[0:1], -1, 0
	s_lshl_b64 s[18:19], s[10:11], 2
	v_and_b32_e32 v85, 7, v0
	s_add_u32 s18, s42, s18
	v_lshrrev_b32_e32 v130, 3, v198
	s_addc_u32 s19, s43, s19
	v_mov_b32_e32 v123, 0
	v_lshlrev_b32_e32 v122, 5, v85
	s_waitcnt vmcnt(13)
	v_or_b32_e32 v10, s10, v130
	s_movk_i32 s9, 0x5800
	s_waitcnt vmcnt(3)
	v_mov_b64_e32 v[50:51], s[44:45]
	v_lshl_add_u64 v[2:3], s[18:19], 0, v[122:123]
	v_mad_u64_u32 v[10:11], s[18:19], v10, s9, v[50:51]
	s_lshl_b32 s10, s20, 2
	v_lshl_add_u64 v[10:11], v[10:11], 0, s[10:11]
	v_lshlrev_b32_e32 v82, 4, v85
	v_mov_b32_e32 v83, v123
	s_add_i32 s6, s6, s7
	v_lshl_add_u64 v[18:19], v[10:11], 0, v[82:83]
	s_mov_b32 s10, 0x2c000
	s_min_i32 s6, s6, 0xaff
	v_add_co_u32_e32 v14, vcc, s10, v18
	s_mul_hi_i32 s7, s6, 0x2e8ba2e9
	s_nop 0
	v_addc_co_u32_e32 v15, vcc, 0, v19, vcc
	s_mov_b32 s11, 0x58000
	s_lshr_b32 s24, s7, 31
	s_ashr_i32 s7, s7, 5
	v_add_co_u32_e32 v20, vcc, s11, v18
	s_add_i32 s7, s7, s24
	s_nop 0
	v_addc_co_u32_e32 v21, vcc, 0, v19, vcc
	s_mov_b32 s18, 0x84000
	s_mul_i32 s24, s7, 0xb0
	v_mov_b32_e32 v32, s45
	v_mov_b32_e32 v33, s44
	v_add_co_u32_e32 v26, vcc, s18, v18
	s_sub_i32 s24, s6, s24
	v_cndmask_b32_e64 v7, v3, v32, s[0:1]
	v_cndmask_b32_e64 v6, v2, v33, s[0:1]
	v_addc_co_u32_e32 v27, vcc, 0, v19, vcc
	s_mov_b32 s19, 0xb0000
	s_lshl_b32 s6, s7, 6
	s_bfe_i32 s7, s24, 0x10002
	s_lshl_b32 s25, s24, 4
	global_load_dwordx4 v[2:5], v[6:7], off offset:16
	s_nop 0
	global_load_dwordx4 v[6:9], v[6:7], off
	s_nop 0
	global_load_dwordx4 v[10:13], v[18:19], off
	s_nop 0
	global_load_dwordx4 v[14:17], v[14:15], off
	s_nop 0
	global_load_dwordx4 v[22:25], v[20:21], off
	s_nop 0
	global_load_dwordx4 v[26:29], v[26:27], off
	v_add_co_u32_e32 v20, vcc, s19, v18
	s_and_b32 s7, s7, 0xb00
	s_and_b32 s25, s25, 0xffffff80
	s_lshl_b32 s24, s24, 5
	v_addc_co_u32_e32 v21, vcc, 0, v19, vcc
	s_mov_b32 s20, 0xdc000
	s_add_i32 s7, s7, s25
	s_and_b32 s24, s24, 0x60
	v_add_co_u32_e32 v30, vcc, s20, v18
	s_or_b32 s24, s7, s24
	s_ashr_i32 s7, s6, 31
	v_addc_co_u32_e32 v31, vcc, 0, v19, vcc
	s_mov_b32 s21, 0x108000
	s_lshl_b64 s[26:27], s[6:7], 2
	global_load_dwordx4 v[34:37], v[20:21], off
	global_load_dwordx4 v[38:41], v[30:31], off
	v_add_co_u32_e32 v20, vcc, s21, v18
	s_add_u32 s26, s42, s26
	v_or_b32_e32 v52, s6, v130
	v_addc_co_u32_e32 v21, vcc, 0, v19, vcc
	s_mov_b32 s22, 0x134000
	s_addc_u32 s27, s43, s27
	v_mad_i64_i32 v[50:51], s[6:7], v52, s9, v[50:51]
	s_ashr_i32 s25, s24, 31
	v_add_co_u32_e32 v18, vcc, s22, v18
	v_lshl_add_u64 v[50:51], s[24:25], 2, v[50:51]
	s_nop 0
	v_addc_co_u32_e32 v19, vcc, 0, v19, vcc
	v_lshl_add_u64 v[74:75], v[50:51], 0, v[82:83]
	s_waitcnt vmcnt(10)
	v_add_co_u32_e32 v54, vcc, s10, v74
	global_load_dwordx4 v[42:45], v[20:21], off
	global_load_dwordx4 v[46:49], v[18:19], off
	v_addc_co_u32_e32 v55, vcc, 0, v75, vcc
	s_waitcnt vmcnt(11)
	v_add_co_u32_e32 v58, vcc, s11, v74
	v_lshl_add_u64 v[18:19], s[26:27], 0, v[122:123]
	s_nop 0
	v_addc_co_u32_e32 v59, vcc, 0, v75, vcc
	s_waitcnt vmcnt(10)
	v_add_co_u32_e32 v62, vcc, s18, v74
	v_cndmask_b32_e64 v31, v19, v32, s[0:1]
	s_nop 0
	v_addc_co_u32_e32 v63, vcc, 0, v75, vcc
	v_add_co_u32_e32 v66, vcc, s19, v74
	v_cndmask_b32_e64 v30, v18, v33, s[0:1]
	s_nop 0
	v_addc_co_u32_e32 v67, vcc, 0, v75, vcc
	v_add_co_u32_e32 v70, vcc, s20, v74
	global_load_dwordx4 v[18:21], v[30:31], off offset:16
	s_nop 0
	global_load_dwordx4 v[30:33], v[30:31], off
	v_addc_co_u32_e32 v71, vcc, 0, v75, vcc
	v_add_co_u32_e32 v76, vcc, s21, v74
	global_load_dwordx4 v[50:53], v[74:75], off
	s_nop 0
	global_load_dwordx4 v[54:57], v[54:55], off
	v_addc_co_u32_e32 v77, vcc, 0, v75, vcc
	v_add_co_u32_e32 v78, vcc, s22, v74
	global_load_dwordx4 v[58:61], v[58:59], off
	s_nop 0
	global_load_dwordx4 v[62:65], v[62:63], off
	v_addc_co_u32_e32 v79, vcc, 0, v75, vcc
	global_load_dwordx4 v[66:69], v[66:67], off
	s_nop 0
	global_load_dwordx4 v[70:73], v[70:71], off
	s_nop 0
	global_load_dwordx4 v[74:77], v[76:77], off
	s_nop 0
	global_load_dwordx4 v[78:81], v[78:79], off
	v_lshlrev_b32_e32 v84, 3, v85
	v_lshlrev_b32_e32 v86, 2, v85
	v_mul_u32_u24_e32 v85, 0x420, v85
	v_lshlrev_b32_e32 v87, 2, v130
	v_add_u32_e32 v82, s5, v82
	v_add3_u32 v134, s5, v85, v87
	s_mul_i32 s5, s71, 24
	s_add_i32 s5, s5, s76
	s_lshl_b32 s6, s4, 5
	s_sub_i32 s24, s5, s6
	s_add_i32 s5, s2, s71
	s_lshl_b32 s5, s5, 3
	s_lshl_b32 s6, s4, 4
	s_sub_i32 s25, s5, s6
	s_lshl_b32 s5, s71, 5
	s_add_i32 s5, s5, s76
	s_mul_i32 s6, s4, 40
	s_sub_i32 s26, s5, s6
	s_lshl_b32 s5, s71, 4
	v_mul_u32_u24_e32 v83, 0x84, v130
	s_add_i32 s5, s5, s76
	s_mul_i32 s4, s4, 24
	v_or_b32_e32 v131, 8, v130
	v_or_b32_e32 v132, 16, v130
	v_or_b32_e32 v133, 24, v130
	v_lshl_add_u64 v[124:125], s[42:43], 0, v[122:123]
	s_mul_i32 s23, s23, 24
	s_sub_i32 s27, s5, s4
	v_lshlrev_b32_e32 v122, 2, v86
	v_lshlrev_b32_e32 v126, 1, v84
	v_add_u32_e32 v135, v82, v83
	s_waitcnt vmcnt(10)
	s_waitcnt vmcnt(0)
	s_branch .LBB0_795

; #define CONV_JOB(it_) conv_job<LIST>((it_) < n ? (it_) : n - 1, P)
; __device__ __forceinline__ void conv_fetch(const ConvJob& j, int lane, ConvSet& s) {
;     const int k0 = 64 * j.kb; int cnt; const int src = vgroup_src(j.kind, j.g, cnt);
;     const int ks = lane >> 3, n4 = (lane & 7) * 4, c = lane & 7; const bool okc = n4 < cnt;
;     const float* gp = j.gain ? j.gain + k0 + 8 * c : j.W;
;     s.g0 = *(const f32x4*)gp; s.g1 = *(const f32x4*)(gp + 4);
;     const float* wp = j.W + (size_t)(k0 + ks) * j.Norig + src + (okc ? n4 : 0);
; #pragma unroll
;     for (int i = 0; i < 8; ++i) s.v[i] = *(const f32x4*)(wp + (size_t)(8 * i) * j.Norig);
; }
; template <int LIST> __device__ __forceinline__ void convert_list(int first, int stride, const Params& P, LAS float* scr, int lane) {
;     ...
;         conv_fetch(CONV_JOB(it + 4 * stride), lane, B); if (it + 2 * stride < n) conv_emit(CONV_JOB(it + 2 * stride), lane, C, scr);
;     }
.LBB0_797:
	s_add_i32 s6, s26, s28
	s_min_i32 s6, s6, 0xaff
	s_mul_hi_i32 s7, s6, 0x2e8ba2e9
	s_lshr_b32 s30, s7, 31
	s_ashr_i32 s7, s7, 5
	s_add_i32 s7, s7, s30
	s_mul_i32 s30, s7, 0xb0
	s_sub_i32 s30, s6, s30
	s_lshl_b32 s6, s7, 6
	s_bfe_i32 s7, s30, 0x10002
	s_lshl_b32 s31, s30, 4
	s_and_b32 s7, s7, 0xb00
	s_and_b32 s31, s31, 0xffffff80
	s_lshl_b32 s30, s30, 5
	s_add_i32 s7, s7, s31
	s_and_b32 s30, s30, 0x60
	s_or_b32 s30, s7, s30
	s_ashr_i32 s7, s6, 31
	s_waitcnt vmcnt(31)
	v_or_b32_e32 v52, s6, v130
	v_mov_b64_e32 v[50:51], s[44:45]
	v_lshl_add_u64 v[18:19], s[6:7], 2, v[124:125]
	v_mad_i64_i32 v[50:51], s[6:7], v52, s9, v[50:51]
	s_ashr_i32 s31, s30, 31
	v_lshl_add_u64 v[50:51], s[30:31], 2, v[50:51]
	s_waitcnt vmcnt(25)
	v_lshl_add_u64 v[74:75], v[50:51], 0, v[122:123]
	v_add_co_u32_e32 v54, vcc, s10, v74
	v_mov_b32_e32 v20, s45
	s_nop 0
	v_addc_co_u32_e32 v55, vcc, 0, v75, vcc
	v_add_co_u32_e32 v58, vcc, s11, v74
	v_cndmask_b32_e64 v31, v19, v20, s[0:1]
	s_nop 0
	v_addc_co_u32_e32 v59, vcc, 0, v75, vcc
	v_add_co_u32_e32 v62, vcc, s18, v74
	v_mov_b32_e32 v19, s44
	s_nop 0
	v_addc_co_u32_e32 v63, vcc, 0, v75, vcc
	v_add_co_u32_e32 v66, vcc, s19, v74
	v_cndmask_b32_e64 v30, v18, v19, s[0:1]
	s_nop 0
	v_addc_co_u32_e32 v67, vcc, 0, v75, vcc
	v_add_co_u32_e32 v70, vcc, 0xdc000, v74
	global_load_dwordx4 v[18:21], v[30:31], off offset:16
	s_nop 0
	global_load_dwordx4 v[30:33], v[30:31], off
	v_addc_co_u32_e32 v71, vcc, 0, v75, vcc
	v_add_co_u32_e32 v76, vcc, 0x108000, v74
	global_load_dwordx4 v[50:53], v[74:75], off
	s_nop 0
	global_load_dwordx4 v[54:57], v[54:55], off
	v_addc_co_u32_e32 v77, vcc, 0, v75, vcc
	s_waitcnt vmcnt(28)
	v_add_co_u32_e32 v78, vcc, 0x134000, v74
	global_load_dwordx4 v[58:61], v[58:59], off
	s_nop 0
	global_load_dwordx4 v[62:65], v[62:63], off
	v_addc_co_u32_e32 v79, vcc, 0, v75, vcc
	global_load_dwordx4 v[66:69], v[66:67], off
	s_nop 0
	global_load_dwordx4 v[70:73], v[70:71], off
	s_nop 0
	global_load_dwordx4 v[74:77], v[76:77], off
	s_nop 0
	global_load_dwordx4 v[78:81], v[78:79], off
	s_andn2_b64 vcc, exec, s[4:5]
	s_cbranch_vccnz .LBB0_794
; #define LAS __attribute__((address_space(3)))
; __device__ __forceinline__ unsigned cvtpk(float lo, float hi) { f32x2_t v = {lo, hi}; bf16x2_t b = __builtin_convertvector(v, bf16x2_t); return __builtin_bit_cast(unsigned, b); }
; #define LDS_WAIT() asm volatile("s_waitcnt lgkmcnt(0)" ::: "memory")
; #define CONV_JOB(it_) conv_job<LIST>((it_) < n ? (it_) : n - 1, P)
; __device__ __forceinline__ void conv_emit(const ConvJob& j, int lane, const ConvSet& s, LAS float* scr) {
;     const int k0 = 64 * j.kb; int cnt; (void)vgroup_src(j.kind, j.g, cnt);
;     const int ks = lane >> 3, n4 = (lane & 7) * 4, c = lane & 7; const bool okc = n4 < cnt;
;     const f32x4 one = (f32x4){1.f, 1.f, 1.f, 1.f}; const f32x4 g0 = j.gain ? s.g0 : one, g1 = j.gain ? s.g1 : one;
; #pragma unroll
;     for (int i = 0; i < 8; ++i) { LAS float* sp = scr + (8 * i + ks) * 33 + n4;
; #pragma unroll
;         for (int e = 0; e < 4; ++e) sp[e] = okc ? s.v[i][e] : 0.f; }
;     LDS_WAIT(); asm volatile("" ::: "memory");
; #pragma unroll
;     for (int q = 0; q < 4; ++q) { const int nn = (lane >> 3) + 8 * q; const LAS float* sr = scr + (8 * c) * 33 + nn;
;         u32x4 o; o.x = cvtpk(sr[0 * 33] * g0[0], sr[1 * 33] * g0[1]); o.y = cvtpk(sr[2 * 33] * g0[2], sr[3 * 33] * g0[3]); o.z = cvtpk(sr[4 * 33] * g1[0], sr[5 * 33] * g1[1]); o.w = cvtpk(sr[6 * 33] * g1[2], sr[7 * 33] * g1[3]);
;         *(u32x4*)(j.WT + (size_t)(j.g * 32 + nn) * j.K + k0 + 8 * c) = o; }
;     LDS_WAIT(); asm volatile("" ::: "memory");
; }
; template <int LIST> __device__ __forceinline__ void convert_list(int first, int stride, const Params& P, LAS float* scr, int lane) {
;     ...
;         conv_fetch(CONV_JOB(it + 4 * stride), lane, B); if (it + 2 * stride < n) conv_emit(CONV_JOB(it + 2 * stride), lane, C, scr);
	s_waitcnt vmcnt(31)
	ds_write2_b32 v135, v90, v91 offset1:1
	ds_write2_b32 v135, v92, v93 offset0:2 offset1:3
	s_waitcnt vmcnt(30)
	ds_write2_b32 v136, v94, v95 offset1:1
	ds_write2_b32 v137, v96, v97 offset1:1
	s_waitcnt vmcnt(29)
	ds_write2_b32 v138, v98, v99 offset1:1
	ds_write2_b32 v139, v100, v101 offset1:1
	s_waitcnt vmcnt(28)
	ds_write2_b32 v140, v102, v103 offset1:1
	ds_write2_b32 v141, v104, v105 offset1:1
	s_waitcnt vmcnt(27)
	ds_write2_b32 v142, v106, v107 offset1:1
	ds_write2_b32 v143, v108, v109 offset1:1
	s_waitcnt vmcnt(26)
	ds_write2_b32 v144, v110, v111 offset1:1
	ds_write2_b32 v145, v112, v113 offset1:1
	s_waitcnt vmcnt(25)
	ds_write2_b32 v146, v114, v115 offset1:1
	ds_write2_b32 v147, v116, v117 offset1:1
	s_waitcnt vmcnt(24)
	ds_write2_b32 v148, v118, v119 offset1:1
	ds_write2_b32 v149, v120, v121 offset1:1
	s_waitcnt lgkmcnt(0)
	ds_read2_b32 v[92:93], v134 offset1:8
	ds_read2_b32 v[96:97], v134 offset0:33 offset1:41
	ds_read2_b32 v[98:99], v134 offset0:66 offset1:74
	ds_read2_b32 v[100:101], v134 offset0:99 offset1:107
	ds_read2_b32 v[102:103], v134 offset0:132 offset1:140
	ds_read2_b32 v[104:105], v134 offset0:165 offset1:173
	ds_read2_b32 v[106:107], v134 offset0:198 offset1:206
	ds_read2_b32 v[108:109], v134 offset0:231 offset1:239
	s_mul_hi_i32 s4, s29, 0x2e8ba2e9
	s_lshr_b32 s5, s4, 31
	s_ashr_i32 s4, s4, 5
	s_add_i32 s4, s4, s5
	v_cndmask_b32_e64 v89, v89, 1.0, s[0:1]
	v_cndmask_b32_e64 v88, v88, 1.0, s[0:1]
	v_cndmask_b32_e64 v87, v87, 1.0, s[0:1]
	v_cndmask_b32_e64 v86, v86, 1.0, s[0:1]
	v_cndmask_b32_e64 v91, v85, 1.0, s[0:1]
	v_cndmask_b32_e64 v90, v84, 1.0, s[0:1]
	v_cndmask_b32_e64 v95, v83, 1.0, s[0:1]
	v_cndmask_b32_e64 v94, v82, 1.0, s[0:1]
	s_waitcnt lgkmcnt(7)
	v_mov_b32_e32 v82, v92
	s_waitcnt lgkmcnt(6)
	v_mov_b32_e32 v83, v96
	s_waitcnt lgkmcnt(5)
	v_mov_b32_e32 v84, v98
	s_waitcnt lgkmcnt(4)
	v_mov_b32_e32 v85, v100
	s_mul_i32 s5, s4, 0xb0
	v_pk_mul_f32 v[82:83], v[86:87], v[82:83]
	v_pk_mul_f32 v[84:85], v[88:89], v[84:85]
	s_sub_i32 s6, s29, s5
	v_cvt_pk_bf16_f32 v82, v82, v83
	v_cvt_pk_bf16_f32 v83, v84, v85
	s_waitcnt lgkmcnt(3)
	v_mov_b32_e32 v84, v102
	s_waitcnt lgkmcnt(2)
	v_mov_b32_e32 v85, v104
	s_waitcnt lgkmcnt(1)
	v_mov_b32_e32 v110, v106
	s_waitcnt lgkmcnt(0)
	v_mov_b32_e32 v111, v108
	v_pk_mul_f32 v[84:85], v[94:95], v[84:85]
	v_pk_mul_f32 v[110:111], v[90:91], v[110:111]
	s_lshl_b32 s6, s6, 5
	v_cvt_pk_bf16_f32 v84, v84, v85
	v_cvt_pk_bf16_f32 v85, v110, v111
	v_or_b32_e32 v110, s6, v130
	s_lshl_b32 s4, s4, 6
	v_ashrrev_i32_e32 v111, 31, v110
	v_readlane_b32 s30, v252, 9
	s_ashr_i32 s5, s4, 31
	v_lshlrev_b64 v[110:111], 11, v[110:111]
	v_readlane_b32 s31, v252, 10
	s_lshl_b64 s[4:5], s[4:5], 1
	v_mov_b32_e32 v127, v123
	v_lshl_add_u64 v[110:111], s[30:31], 0, v[110:111]
	v_lshl_add_u64 v[110:111], v[110:111], 0, s[4:5]
	v_lshl_add_u64 v[110:111], v[110:111], 0, v[126:127]
	v_mov_b32_e32 v96, v93
	v_mov_b32_e32 v100, v99
	global_store_dwordx4 v[110:111], v[82:85], off
	v_mov_b32_e32 v104, v103
	v_mov_b32_e32 v108, v107
	v_pk_mul_f32 v[82:83], v[86:87], v[96:97]
	v_pk_mul_f32 v[84:85], v[88:89], v[100:101]
	v_cvt_pk_bf16_f32 v82, v82, v83
	v_cvt_pk_bf16_f32 v83, v84, v85
	v_pk_mul_f32 v[84:85], v[94:95], v[104:105]
	v_pk_mul_f32 v[92:93], v[90:91], v[108:109]
	v_cvt_pk_bf16_f32 v84, v84, v85
	v_cvt_pk_bf16_f32 v85, v92, v93
	v_or_b32_e32 v92, s6, v131
	v_ashrrev_i32_e32 v93, 31, v92
	v_lshlrev_b64 v[92:93], 11, v[92:93]
	v_lshl_add_u64 v[92:93], s[30:31], 0, v[92:93]
	v_lshl_add_u64 v[92:93], v[92:93], 0, s[4:5]
	v_lshl_add_u64 v[92:93], v[92:93], 0, v[126:127]
	ds_read2_b32 v[96:97], v134 offset0:16 offset1:24
	ds_read2_b32 v[98:99], v134 offset0:49 offset1:57
	global_store_dwordx4 v[92:93], v[82:85], off
	ds_read2_b32 v[92:93], v134 offset0:82 offset1:90
	ds_read2_b32 v[100:101], v134 offset0:115 offset1:123
	ds_read2_b32 v[102:103], v134 offset0:148 offset1:156
	ds_read2_b32 v[104:105], v134 offset0:181 offset1:189
	ds_read2_b32 v[106:107], v134 offset0:214 offset1:222
	ds_read2_b32 v[108:109], v134 offset0:247 offset1:255
	s_waitcnt lgkmcnt(7)
	v_mov_b32_e32 v82, v96
	s_waitcnt lgkmcnt(6)
	v_mov_b32_e32 v83, v98
	s_waitcnt lgkmcnt(5)
	v_mov_b32_e32 v84, v92
	s_waitcnt lgkmcnt(4)
	v_mov_b32_e32 v85, v100
	v_pk_mul_f32 v[82:83], v[86:87], v[82:83]
	v_pk_mul_f32 v[84:85], v[88:89], v[84:85]
	v_cvt_pk_bf16_f32 v82, v82, v83
	v_cvt_pk_bf16_f32 v83, v84, v85
	s_waitcnt lgkmcnt(3)
	v_mov_b32_e32 v84, v102
	s_waitcnt lgkmcnt(2)
	v_mov_b32_e32 v85, v104
	s_waitcnt lgkmcnt(1)
	v_mov_b32_e32 v110, v106
	s_waitcnt lgkmcnt(0)
	v_mov_b32_e32 v111, v108
	v_pk_mul_f32 v[84:85], v[94:95], v[84:85]
	v_pk_mul_f32 v[110:111], v[90:91], v[110:111]
	v_cvt_pk_bf16_f32 v84, v84, v85
	v_cvt_pk_bf16_f32 v85, v110, v111
	v_or_b32_e32 v110, s6, v132
	v_ashrrev_i32_e32 v111, 31, v110
	v_lshlrev_b64 v[110:111], 11, v[110:111]
	v_lshl_add_u64 v[110:111], s[30:31], 0, v[110:111]
	v_lshl_add_u64 v[110:111], v[110:111], 0, s[4:5]
	v_lshl_add_u64 v[110:111], v[110:111], 0, v[126:127]
	v_mov_b32_e32 v98, v97
	v_mov_b32_e32 v100, v93
	global_store_dwordx4 v[110:111], v[82:85], off
	v_mov_b32_e32 v104, v103
	v_mov_b32_e32 v108, v107
	v_pk_mul_f32 v[82:83], v[86:87], v[98:99]
	v_pk_mul_f32 v[84:85], v[88:89], v[100:101]
	v_cvt_pk_bf16_f32 v82, v82, v83
	v_cvt_pk_bf16_f32 v83, v84, v85
	v_pk_mul_f32 v[84:85], v[94:95], v[104:105]
	v_pk_mul_f32 v[86:87], v[90:91], v[108:109]
	v_cvt_pk_bf16_f32 v84, v84, v85
	v_cvt_pk_bf16_f32 v85, v86, v87
	v_or_b32_e32 v86, s6, v133
	v_ashrrev_i32_e32 v87, 31, v86
	v_lshlrev_b64 v[86:87], 11, v[86:87]
	v_lshl_add_u64 v[86:87], s[30:31], 0, v[86:87]
	v_lshl_add_u64 v[86:87], v[86:87], 0, s[4:5]
	v_lshl_add_u64 v[86:87], v[86:87], 0, v[126:127]
	global_store_dwordx4 v[86:87], v[82:85], off
	s_waitcnt lgkmcnt(0)
	s_branch .LBB0_794
.LBB0_802:
	s_barrier

;     __device__ __forceinline__ bool next(int i, Unit& u) const {
;         const long L = (long)(i >> psh) * G + c; if (L >= nwg) return false;
;         int wgid = (int)L; { const int q = nwg / NXCD, r = nwg % NXCD, xcd = wgid % NXCD, off = wgid / NXCD; wgid = (xcd < r ? xcd * (q + 1) : r * (q + 1) + (xcd - r) * q) + off; }
;         const int nig = WGM * nN, gid = wgid / nig, fm = gid * WGM, gsz = (nM - fm) < WGM ? (nM - fm) : WGM;
;         u.pm = fm + ((wgid % nig) % gsz); u.pn = (wgid % nig) / gsz; u.part = i & ((1 << psh) - 1); u.idx = i; return true;
.LBB0_1658:
	s_cmp_lt_i32 s84, 10
	s_cselect_b64 s[4:5], -1, 0
	s_and_b64 s[12:13], s[4:5], s[0:1]
	s_andn2_b64 vcc, exec, s[12:13]
	s_cbranch_vccnz .LBB0_1725
	s_ashr_i32 s3, s2, 31
	s_waitcnt vmcnt(0) lgkmcnt(0)
	v_lshrrev_b32_e32 v254, 6, v0
	v_mov_b64_e32 v[2:3], s[2:3]
	v_mad_i64_i32 v[2:3], s[0:1], v254, s71, v[2:3]
	s_mov_b64 s[0:1], 0x596
	s_ashr_i32 s28, s71, 31
	v_cmp_gt_i64_e32 vcc, s[0:1], v[2:3]
	v_mov_b32_e32 v3, 0
	s_and_saveexec_b64 s[4:5], vcc
	s_cbranch_execz .LBB0_1665
	v_ashrrev_i32_e32 v3, 31, v2
	v_lshrrev_b32_e32 v3, 29, v3
	v_add_u32_e32 v4, v2, v3
	v_and_b32_e32 v3, -8, v4
	v_sub_u32_e32 v3, v2, v3
	v_cmp_lt_i32_e64 s[0:1], 5, v3
	s_and_saveexec_b64 s[6:7], s[0:1]
	s_xor_b64 s[0:1], exec, s[6:7]
	s_movk_i32 s6, 0xb2
	v_mad_u64_u32 v[2:3], s[6:7], v3, s6, 6
	s_or_saveexec_b64 s[0:1], s[0:1]
	v_ashrrev_i32_e32 v4, 3, v4
	s_xor_b64 exec, exec, s[0:1]
	s_movk_i32 s6, 0xb3
	v_mul_lo_u32 v2, v3, s6
	s_or_b64 exec, exec, s[0:1]
	v_add_u32_e32 v2, v2, v4
	s_mov_b32 s0, 0x2e8ba2e9
	v_mul_hi_i32 v3, v2, s0
	v_lshrrev_b32_e32 v4, 31, v3
	v_ashrrev_i32_e32 v3, 4, v3
	v_add_u32_e32 v3, v3, v4
	v_lshlrev_b32_e32 v4, 2, v3
	v_sub_u32_e32 v5, 0x41, v4
	v_min_i32_e32 v5, 4, v5
	v_sub_u32_e32 v6, 0, v5
	v_max_i32_e32 v5, v5, v6
	v_cvt_f32_u32_e32 v6, v5
	s_movk_i32 s0, 0x58
	v_mul_lo_u32 v3, v3, s0
	v_sub_u32_e32 v2, v2, v3
	v_rcp_iflag_f32_e32 v6, v6
	v_sub_u32_e32 v7, 0, v2
	v_ashrrev_i32_e32 v3, 31, v2
	v_max_i32_e32 v2, v2, v7
	v_mul_f32_e32 v6, 0x4f7ffffe, v6
	v_cvt_u32_f32_e32 v6, v6
	v_sub_u32_e32 v7, 0, v5
	v_mul_lo_u32 v7, v7, v6
	v_mul_hi_u32 v7, v6, v7
	v_add_u32_e32 v6, v6, v7
	v_mul_hi_u32 v6, v2, v6
	v_mul_lo_u32 v6, v6, v5
	v_sub_u32_e32 v2, v2, v6
	v_sub_u32_e32 v6, v2, v5
	v_cmp_ge_u32_e64 s[0:1], v2, v5
	s_nop 1
	v_cndmask_b32_e64 v2, v2, v6, s[0:1]
	v_sub_u32_e32 v6, v2, v5
	v_cmp_ge_u32_e64 s[0:1], v2, v5
	s_nop 1
	v_cndmask_b32_e64 v2, v2, v6, s[0:1]
	v_xor_b32_e32 v2, v2, v3
	v_sub_u32_e32 v2, v2, v3
	v_add_lshl_u32 v3, v4, v2, 8
.LBB0_1665:
	s_or_b64 exec, exec, s[4:5]
	v_and_b32_e32 v4, 63, v0
	v_or_b32_e32 v2, v3, v4
	v_ashrrev_i32_e32 v3, 31, v2
	v_lshlrev_b64 v[2:3], 6, v[2:3]
	v_lshl_add_u64 v[14:15], s[10:11], 0, v[2:3]
	s_mov_b64 s[0:1], 0x1000
	v_lshl_add_u64 v[30:31], v[14:15], 0, s[0:1]
	v_lshl_add_u64 v[46:47], v[30:31], 0, s[0:1]
	v_lshl_add_u64 v[62:63], v[46:47], 0, s[0:1]
	v_lshlrev_b32_e32 v66, 10, v254
	v_lshl_add_u32 v66, v4, 2, v66
	v_add_u32_e32 v66, 0x20800, v66
	global_load_dwordx4 v[2:5], v[14:15], off offset:48
	global_load_dwordx4 v[6:9], v[14:15], off offset:32
	global_load_dwordx4 v[10:13], v[14:15], off offset:16
	s_nop 0
	global_load_dwordx4 v[14:17], v[14:15], off
	global_load_dwordx4 v[18:21], v[30:31], off offset:48
	global_load_dwordx4 v[22:25], v[30:31], off offset:32
	global_load_dwordx4 v[26:29], v[30:31], off offset:16
	s_nop 0
	global_load_dwordx4 v[30:33], v[30:31], off
	global_load_dwordx4 v[34:37], v[46:47], off offset:48
	global_load_dwordx4 v[38:41], v[46:47], off offset:32
	global_load_dwordx4 v[42:45], v[46:47], off offset:16
	s_nop 0
	global_load_dwordx4 v[46:49], v[46:47], off
	global_load_dwordx4 v[50:53], v[62:63], off offset:48
	global_load_dwordx4 v[54:57], v[62:63], off offset:32
	global_load_dwordx4 v[58:61], v[62:63], off offset:16
	s_nop 0
	global_load_dwordx4 v[62:65], v[62:63], off
	s_waitcnt vmcnt(12)
	v_mov_b32_e32 v68, v15
	v_mov_b32_e32 v69, v16
	v_mov_b32_e32 v15, v17
	v_mov_b32_e32 v16, v11
	v_mov_b32_e32 v17, v12
	v_mov_b32_e32 v11, v13
	v_pk_add_f32 v[14:15], v[68:69], v[14:15]
	v_pk_add_f32 v[10:11], v[16:17], v[10:11]
	v_pk_add_f32 v[14:15], v[14:15], v[14:15] op_sel:[0,1] op_sel_hi:[1,0]
	v_pk_add_f32 v[10:11], v[10:11], v[10:11] op_sel:[0,1] op_sel_hi:[1,0]
	v_add_f32_e32 v6, v6, v7
	v_add_f32_e32 v8, v8, v9
	v_mov_b32_e32 v15, v2
	v_mov_b32_e32 v11, v3
	v_mov_b32_e32 v7, v4
	v_mov_b32_e32 v9, v5
	v_pk_add_f32 v[2:3], v[14:15], v[10:11]
	v_pk_add_f32 v[4:5], v[6:7], v[8:9]
	s_nop 0
	v_pk_add_f32 v[2:3], v[2:3], v[4:5]
	s_nop 0
	v_add_f32_e32 v2, v2, v3
	v_mov_b32_e32 v3, 0x358637bd
	v_fmac_f32_e32 v3, 0x3a800000, v2
	v_rsq_f32_e32 v2, v3
	ds_write_b32 v66, v2
	s_waitcnt vmcnt(8)
	v_mov_b32_e32 v2, v31
	v_mov_b32_e32 v3, v32
	v_mov_b32_e32 v31, v33
	v_mov_b32_e32 v4, v27
	v_mov_b32_e32 v5, v28
	v_mov_b32_e32 v27, v29
	v_pk_add_f32 v[2:3], v[2:3], v[30:31]
	v_pk_add_f32 v[4:5], v[4:5], v[26:27]
	v_pk_add_f32 v[2:3], v[2:3], v[2:3] op_sel:[0,1] op_sel_hi:[1,0]
	v_pk_add_f32 v[4:5], v[4:5], v[4:5] op_sel:[0,1] op_sel_hi:[1,0]
	v_add_f32_e32 v6, v22, v23
	v_add_f32_e32 v8, v24, v25
	v_mov_b32_e32 v3, v18
	v_mov_b32_e32 v5, v19
	v_mov_b32_e32 v7, v20
	v_mov_b32_e32 v9, v21
	v_pk_add_f32 v[2:3], v[2:3], v[4:5]
	v_pk_add_f32 v[4:5], v[6:7], v[8:9]
	s_nop 0
	v_pk_add_f32 v[2:3], v[2:3], v[4:5]
	s_nop 0
	v_add_f32_e32 v2, v2, v3
	v_mov_b32_e32 v3, 0x358637bd
	v_fmac_f32_e32 v3, 0x3a800000, v2
	v_rsq_f32_e32 v2, v3
	ds_write_b32 v66, v2 offset:256
	s_waitcnt vmcnt(4)
	v_mov_b32_e32 v2, v47
	v_mov_b32_e32 v3, v48
	v_mov_b32_e32 v47, v49
	v_mov_b32_e32 v4, v43
	v_mov_b32_e32 v5, v44
	v_mov_b32_e32 v43, v45
	v_pk_add_f32 v[2:3], v[2:3], v[46:47]
	v_pk_add_f32 v[4:5], v[4:5], v[42:43]
	v_pk_add_f32 v[2:3], v[2:3], v[2:3] op_sel:[0,1] op_sel_hi:[1,0]
	v_pk_add_f32 v[4:5], v[4:5], v[4:5] op_sel:[0,1] op_sel_hi:[1,0]
	v_add_f32_e32 v6, v38, v39
	v_add_f32_e32 v8, v40, v41
	v_mov_b32_e32 v3, v34
	v_mov_b32_e32 v5, v35
	v_mov_b32_e32 v7, v36
	v_mov_b32_e32 v9, v37
	v_pk_add_f32 v[2:3], v[2:3], v[4:5]
	v_pk_add_f32 v[4:5], v[6:7], v[8:9]
	s_nop 0
	v_pk_add_f32 v[2:3], v[2:3], v[4:5]
	s_nop 0
	v_add_f32_e32 v2, v2, v3
	v_mov_b32_e32 v3, 0x358637bd
	v_fmac_f32_e32 v3, 0x3a800000, v2
	v_rsq_f32_e32 v2, v3
	ds_write_b32 v66, v2 offset:512
	s_waitcnt vmcnt(0)
	v_mov_b32_e32 v2, v63
	v_mov_b32_e32 v3, v64
	v_mov_b32_e32 v63, v65
	v_mov_b32_e32 v4, v59
	v_mov_b32_e32 v5, v60
	v_mov_b32_e32 v59, v61
	v_pk_add_f32 v[2:3], v[2:3], v[62:63]
	v_pk_add_f32 v[4:5], v[4:5], v[58:59]
	v_pk_add_f32 v[2:3], v[2:3], v[2:3] op_sel:[0,1] op_sel_hi:[1,0]
	v_pk_add_f32 v[4:5], v[4:5], v[4:5] op_sel:[0,1] op_sel_hi:[1,0]
	v_add_f32_e32 v6, v54, v55
	v_add_f32_e32 v8, v56, v57
	v_mov_b32_e32 v3, v50
	v_mov_b32_e32 v5, v51
	v_mov_b32_e32 v7, v52
	v_mov_b32_e32 v9, v53
	v_pk_add_f32 v[2:3], v[2:3], v[4:5]
	v_pk_add_f32 v[4:5], v[6:7], v[8:9]
	s_nop 0
	v_pk_add_f32 v[2:3], v[2:3], v[4:5]
	s_nop 0
	v_add_f32_e32 v2, v2, v3
	v_mov_b32_e32 v3, 0x358637bd
	v_fmac_f32_e32 v3, 0x3a800000, v2
	v_rsq_f32_e32 v2, v3
	ds_write_b32 v66, v2 offset:768
; #define LAS __attribute__((address_space(3)))
; __device__ __forceinline__ unsigned cvtpk(float lo, float hi) { f32x2_t v = {lo, hi}; bf16x2_t b = __builtin_convertvector(v, bf16x2_t); return __builtin_bit_cast(unsigned, b); }
; #define LDS_WAIT() asm volatile("s_waitcnt lgkmcnt(0)" ::: "memory")
; __device__ __forceinline__ void conv_fetch(const ConvJob& j, int lane, ConvSet& s) {
;     const int k0 = 64 * j.kb; int cnt; const int src = vgroup_src(j.kind, j.g, cnt);
;     const int ks = lane >> 3, n4 = (lane & 7) * 4, c = lane & 7; const bool okc = n4 < cnt;
;     const float* gp = j.gain ? j.gain + k0 + 8 * c : j.W;
;     s.g0 = *(const f32x4*)gp; s.g1 = *(const f32x4*)(gp + 4);
;     const float* wp = j.W + (size_t)(k0 + ks) * j.Norig + src + (okc ? n4 : 0);
; #pragma unroll
;     for (int i = 0; i < 8; ++i) s.v[i] = *(const f32x4*)(wp + (size_t)(8 * i) * j.Norig);
; }
; __device__ __forceinline__ void conv_emit(const ConvJob& j, int lane, const ConvSet& s, LAS float* scr) {
;     const int k0 = 64 * j.kb; int cnt; (void)vgroup_src(j.kind, j.g, cnt);
;     const int ks = lane >> 3, n4 = (lane & 7) * 4, c = lane & 7; const bool okc = n4 < cnt;
;     const f32x4 one = (f32x4){1.f, 1.f, 1.f, 1.f}; const f32x4 g0 = j.gain ? s.g0 : one, g1 = j.gain ? s.g1 : one;
; #pragma unroll
;     for (int i = 0; i < 8; ++i) { LAS float* sp = scr + (8 * i + ks) * 33 + n4;
; #pragma unroll
;         for (int e = 0; e < 4; ++e) sp[e] = okc ? s.v[i][e] : 0.f; }
;     LDS_WAIT(); asm volatile("" ::: "memory");
; #pragma unroll
;     for (int q = 0; q < 4; ++q) { const int nn = (lane >> 3) + 8 * q; const LAS float* sr = scr + (8 * c) * 33 + nn;
;         u32x4 o; o.x = cvtpk(sr[0 * 33] * g0[0], sr[1 * 33] * g0[1]); o.y = cvtpk(sr[2 * 33] * g0[2], sr[3 * 33] * g0[3]); o.z = cvtpk(sr[4 * 33] * g1[0], sr[5 * 33] * g1[1]); o.w = cvtpk(sr[6 * 33] * g1[2], sr[7 * 33] * g1[3]);
;         *(u32x4*)(j.WT + (size_t)(j.g * 32 + nn) * j.K + k0 + 8 * c) = o; }
;     LDS_WAIT(); asm volatile("" ::: "memory");
; }
; template <int LIST> __device__ __forceinline__ void convert_list(int first, int stride, const Params& P, LAS float* scr, int lane) {
;     constexpr int n = conv_count<LIST>();
;     if (first >= n) return;
;     ConvSet A, B, C;
;     ...
;     conv_fetch(CONV_JOB(first), lane, A); conv_fetch(CONV_JOB(first + stride), lane, B);
;     CONV_LANDED(A); CONV_LANDED(B);
.LBB0_1688:
	v_readlane_b32 s0, v252, 12
	v_readlane_b32 s1, v252, 13
	s_andn2_b64 vcc, exec, s[0:1]
	s_waitcnt lgkmcnt(0)
	s_barrier
	s_cbranch_vccnz .LBB0_1701
	s_abs_i32 s0, s71
	s_waitcnt vmcnt(15)
	v_cvt_f32_u32_e32 v2, s0
	s_sub_i32 s1, 0, s0
	v_rcp_iflag_f32_e32 v2, v2
	s_nop 0
	v_mul_f32_e32 v2, 0x4f7ffffe, v2
	v_cvt_u32_f32_e32 v2, v2
	s_nop 0
	v_readfirstlane_b32 s4, v2
	s_mul_i32 s1, s1, s4
	s_mul_hi_u32 s1, s4, s1
	s_add_i32 s4, s4, s1
	s_mul_hi_u32 s1, s4, 0x596
	s_mul_i32 s1, s1, s0
	s_sub_i32 s1, 0x596, s1
	s_sub_i32 s4, s1, s0
	s_cmp_ge_u32 s1, s0
	s_cselect_b32 s1, s4, s1
	s_sub_i32 s4, s1, s0
	s_cmp_ge_u32 s1, s0
	s_cselect_b32 s0, s4, s1
	s_sub_i32 s1, s2, s0
	s_cmp_lt_i32 s1, 0
	s_cbranch_scc1 .LBB0_1700
	s_lshl_b32 s1, s1, 3
	v_readlane_b32 s4, v252, 11
	s_add_i32 s19, s1, s4
	s_cmpk_gt_i32 s19, 0x57f
	s_cbranch_scc1 .LBB0_1700
	s_lshl_b32 s4, s19, 1
	s_and_b32 s4, s4, 0x7fffffc0
	v_lshrrev_b32_e32 v102, 3, v198
	v_mov_b32_e32 v99, 0
	v_or_b32_e32 v98, s4, v102
	v_lshlrev_b64 v[2:3], 12, v[98:99]
	s_lshl_b32 s4, s19, 7
	s_mov_b32 s5, 0
	v_and_b32_e32 v75, 7, v0
	v_lshl_add_u64 v[2:3], s[46:47], 0, v[2:3]
	s_and_b32 s4, s4, 0xf80
	v_lshl_add_u64 v[2:3], v[2:3], 0, s[4:5]
	v_lshlrev_b32_e32 v98, 4, v75
	s_sub_i32 s16, s71, s0
	s_waitcnt vmcnt(9)
	v_lshl_add_u64 v[26:27], v[2:3], 0, v[98:99]
	s_mov_b32 s4, 0x8000
	s_lshl_b32 s1, s16, 3
	v_add_co_u32_e32 v6, vcc, s4, v26
	s_mov_b32 s5, 0x10000
	s_nop 0
	v_addc_co_u32_e32 v7, vcc, 0, v27, vcc
	s_add_i32 s1, s19, s1
	v_add_co_u32_e32 v10, vcc, s5, v26
	s_min_i32 s1, s1, 0x57f
	s_nop 0
	v_addc_co_u32_e32 v11, vcc, 0, v27, vcc
	s_mov_b32 s6, 0x18000
	s_ashr_i32 s11, s1, 31
	v_add_co_u32_e32 v14, vcc, s6, v26
	s_lshr_b32 s11, s11, 27
	s_nop 0
	v_addc_co_u32_e32 v15, vcc, 0, v27, vcc
	s_mov_b32 s7, 0x20000
	s_add_i32 s11, s1, s11
	v_add_co_u32_e32 v18, vcc, s7, v26
	s_and_b32 s14, s11, 0x7ffffe0
	s_lshl_b32 s11, s11, 1
	v_addc_co_u32_e32 v19, vcc, 0, v27, vcc
	s_mov_b32 s8, 0x28000
	s_andn2_b32 s11, s11, 63
	v_add_co_u32_e32 v22, vcc, s8, v26
	s_waitcnt vmcnt(7)
	v_or_b32_e32 v34, s11, v102
	v_addc_co_u32_e32 v23, vcc, 0, v27, vcc
	s_mov_b32 s9, 0x30000
	s_sub_i32 s1, s1, s14
	v_ashrrev_i32_e32 v35, 31, v34
	v_add_co_u32_e32 v28, vcc, s9, v26
	s_lshl_b32 s14, s1, 5
	v_lshlrev_b64 v[34:35], 12, v[34:35]
	v_addc_co_u32_e32 v29, vcc, 0, v27, vcc
	s_mov_b32 s10, 0x38000
	v_lshl_add_u64 v[34:35], s[46:47], 0, v[34:35]
	s_ashr_i32 s15, s14, 31
	v_add_co_u32_e32 v30, vcc, s10, v26
	v_lshl_add_u64 v[34:35], s[14:15], 2, v[34:35]
	s_nop 0
	v_addc_co_u32_e32 v31, vcc, 0, v27, vcc
	s_waitcnt vmcnt(1)
	v_lshl_add_u64 v[58:59], v[34:35], 0, v[98:99]
	v_add_co_u32_e32 v38, vcc, s4, v58
	global_load_dwordx4 v[66:69], v99, s[46:47] offset:16
	global_load_dwordx4 v[70:73], v99, s[46:47]
	v_addc_co_u32_e32 v39, vcc, 0, v59, vcc
	v_add_co_u32_e32 v42, vcc, s5, v58
	global_load_dwordx4 v[2:5], v[26:27], off
	s_nop 0
	global_load_dwordx4 v[6:9], v[6:7], off
	v_addc_co_u32_e32 v43, vcc, 0, v59, vcc
	v_add_co_u32_e32 v46, vcc, s6, v58
	global_load_dwordx4 v[10:13], v[10:11], off
	s_nop 0
	global_load_dwordx4 v[14:17], v[14:15], off
	v_addc_co_u32_e32 v47, vcc, 0, v59, vcc
	v_add_co_u32_e32 v50, vcc, s7, v58
	global_load_dwordx4 v[18:21], v[18:19], off
	s_nop 0
	global_load_dwordx4 v[22:25], v[22:23], off
	v_addc_co_u32_e32 v51, vcc, 0, v59, vcc
	v_add_co_u32_e32 v54, vcc, s8, v58
	global_load_dwordx4 v[26:29], v[28:29], off
	s_nop 0
	global_load_dwordx4 v[30:33], v[30:31], off
	v_addc_co_u32_e32 v55, vcc, 0, v59, vcc
	v_add_co_u32_e32 v60, vcc, s9, v58
	global_load_dwordx4 v[34:37], v[58:59], off
	s_nop 0
	global_load_dwordx4 v[38:41], v[38:39], off
	v_addc_co_u32_e32 v61, vcc, 0, v59, vcc
	s_waitcnt vmcnt(12)
	v_add_co_u32_e32 v62, vcc, s10, v58
	global_load_dwordx4 v[42:45], v[42:43], off
	s_nop 0
	global_load_dwordx4 v[46:49], v[46:47], off
	v_addc_co_u32_e32 v63, vcc, 0, v59, vcc
	global_load_dwordx4 v[50:53], v[50:51], off
	s_nop 0
	global_load_dwordx4 v[54:57], v[54:55], off
	s_nop 0
	global_load_dwordx4 v[58:61], v[60:61], off
	s_nop 0
	global_load_dwordx4 v[62:65], v[62:63], off
	v_readlane_b32 s1, v252, 11
	s_lshl_b32 s1, s1, 14
	s_add_i32 s1, s1, 0
	s_waitcnt vmcnt(8)
	s_waitcnt vmcnt(0)
	v_mul_u32_u24_e32 v69, 0x420, v75
	v_lshlrev_b32_e32 v70, 2, v102
	v_add_u32_e32 v67, s1, v98
	v_add3_u32 v106, s1, v69, v70
	s_mul_i32 s1, s19, 0x2c000
	s_mul_i32 s14, s16, 24
	v_mov_b32_e32 v69, s1
	s_lshl_b32 s1, s0, 4
	s_add_i32 s1, s14, s1
	s_lshl_b32 s17, s71, 4
	v_lshlrev_b32_e32 v74, 2, v75
	v_mul_u32_u24_e32 v68, 0x84, v102
	v_lshlrev_b32_e32 v66, 3, v75
	s_movk_i32 s15, 0x1600
	s_sub_i32 s17, s1, s17
	s_add_i32 s1, s14, s82
	s_lshl_b32 s0, s0, 3
	s_lshl_b32 s11, s16, 4
	v_or_b32_e32 v103, 8, v102
	v_or_b32_e32 v104, 16, v102
	v_or_b32_e32 v105, 24, v102
	v_mad_u32_u24 v107, v102, s15, v69
	s_mul_i32 s16, s16, 0x420000
	s_sub_i32 s18, s1, s0
	v_lshlrev_b32_e32 v98, 2, v74
	v_lshlrev_b32_e32 v100, 1, v66
	v_add_u32_e32 v108, v67, v68
	s_branch .LBB0_1693

; #define LAS __attribute__((address_space(3)))
; __device__ __forceinline__ unsigned cvtpk(float lo, float hi) { f32x2_t v = {lo, hi}; bf16x2_t b = __builtin_convertvector(v, bf16x2_t); return __builtin_bit_cast(unsigned, b); }
; #define LDS_WAIT() asm volatile("s_waitcnt lgkmcnt(0)" ::: "memory")
; #define CONV_JOB(it_) conv_job<LIST>((it_) < n ? (it_) : n - 1, P)
; __device__ __forceinline__ void conv_emit(const ConvJob& j, int lane, const ConvSet& s, LAS float* scr) {
;     const int k0 = 64 * j.kb; int cnt; (void)vgroup_src(j.kind, j.g, cnt);
;     const int ks = lane >> 3, n4 = (lane & 7) * 4, c = lane & 7; const bool okc = n4 < cnt;
;     const f32x4 one = (f32x4){1.f, 1.f, 1.f, 1.f}; const f32x4 g0 = j.gain ? s.g0 : one, g1 = j.gain ? s.g1 : one;
; #pragma unroll
;     for (int i = 0; i < 8; ++i) { LAS float* sp = scr + (8 * i + ks) * 33 + n4;
; #pragma unroll
;         for (int e = 0; e < 4; ++e) sp[e] = okc ? s.v[i][e] : 0.f; }
;     LDS_WAIT(); asm volatile("" ::: "memory");
; #pragma unroll
;     for (int q = 0; q < 4; ++q) { const int nn = (lane >> 3) + 8 * q; const LAS float* sr = scr + (8 * c) * 33 + nn;
;         u32x4 o; o.x = cvtpk(sr[0 * 33] * g0[0], sr[1 * 33] * g0[1]); o.y = cvtpk(sr[2 * 33] * g0[2], sr[3 * 33] * g0[3]); o.z = cvtpk(sr[4 * 33] * g1[0], sr[5 * 33] * g1[1]); o.w = cvtpk(sr[6 * 33] * g1[2], sr[7 * 33] * g1[3]);
;         *(u32x4*)(j.WT + (size_t)(j.g * 32 + nn) * j.K + k0 + 8 * c) = o; }
;     LDS_WAIT(); asm volatile("" ::: "memory");
; }
; template <int LIST> __device__ __forceinline__ void convert_list(int first, int stride, const Params& P, LAS float* scr, int lane) {
;     constexpr int n = conv_count<LIST>();
;     if (first >= n) return;
;     ConvSet A, B, C;
;     ...
;     conv_fetch(CONV_JOB(first), lane, A); conv_fetch(CONV_JOB(first + stride), lane, B);
;     CONV_LANDED(A); CONV_LANDED(B);
;     for (int it = first; it < n; it += 3 * stride) {
;         conv_fetch(CONV_JOB(it + 2 * stride), lane, C); conv_emit(CONV_JOB(it), lane, A, scr);
;         conv_fetch(CONV_JOB(it + 3 * stride), lane, A); if (it + stride < n) conv_emit(CONV_JOB(it + stride), lane, B, scr);
;         conv_fetch(CONV_JOB(it + 4 * stride), lane, B); if (it + 2 * stride < n) conv_emit(CONV_JOB(it + 2 * stride), lane, C, scr);
;     }
.LBB0_1695:
	s_add_i32 s19, s18, s19
	s_min_i32 s19, s19, 0x57f
	s_ashr_i32 s22, s19, 31
	s_lshr_b32 s22, s22, 27
	s_add_i32 s22, s19, s22
	s_and_b32 s23, s22, 0x7ffffe0
	s_lshl_b32 s22, s22, 1
	s_sub_i32 s19, s19, s23
	s_and_b32 s23, s22, 0xffffffc0
	s_waitcnt vmcnt(27)
	v_or_b32_e32 v34, s23, v102
	v_ashrrev_i32_e32 v35, 31, v34
	s_lshl_b32 s22, s19, 5
	v_lshlrev_b64 v[34:35], 12, v[34:35]
	v_lshl_add_u64 v[34:35], s[46:47], 0, v[34:35]
	s_ashr_i32 s23, s22, 31
	v_lshl_add_u64 v[34:35], s[22:23], 2, v[34:35]
	s_waitcnt vmcnt(21)
	v_lshl_add_u64 v[58:59], v[34:35], 0, v[98:99]
	v_add_co_u32_e32 v38, vcc, s4, v58
	s_nop 1
	v_addc_co_u32_e32 v39, vcc, 0, v59, vcc
	v_add_co_u32_e32 v42, vcc, s5, v58
	global_load_dwordx4 v[34:37], v[58:59], off
	s_nop 0
	global_load_dwordx4 v[38:41], v[38:39], off
	v_addc_co_u32_e32 v43, vcc, 0, v59, vcc
	v_add_co_u32_e32 v46, vcc, s6, v58
	s_nop 1
	v_addc_co_u32_e32 v47, vcc, 0, v59, vcc
	v_add_co_u32_e32 v50, vcc, s7, v58
	global_load_dwordx4 v[42:45], v[42:43], off
	s_nop 0
	global_load_dwordx4 v[46:49], v[46:47], off
	v_addc_co_u32_e32 v51, vcc, 0, v59, vcc
	v_add_co_u32_e32 v54, vcc, 0x28000, v58
	s_nop 1
	v_addc_co_u32_e32 v55, vcc, 0, v59, vcc
	v_add_co_u32_e32 v60, vcc, 0x30000, v58
	global_load_dwordx4 v[50:53], v[50:51], off
	s_nop 0
	global_load_dwordx4 v[54:57], v[54:55], off
	v_addc_co_u32_e32 v61, vcc, 0, v59, vcc
	s_waitcnt vmcnt(26)
	v_add_co_u32_e32 v62, vcc, 0x38000, v58
	s_nop 1
	v_addc_co_u32_e32 v63, vcc, 0, v59, vcc
	global_load_dwordx4 v[58:61], v[60:61], off
	s_nop 0
	global_load_dwordx4 v[62:65], v[62:63], off
	s_andn2_b64 vcc, exec, s[0:1]
	s_cbranch_vccnz .LBB0_1692
	s_ashr_i32 s0, s20, 31
	s_lshr_b32 s0, s0, 27
	s_add_i32 s0, s20, s0
	s_waitcnt vmcnt(27)
	ds_write2_b32 v108, v66, v67 offset1:1
	ds_write2_b32 v108, v68, v69 offset0:2 offset1:3
	s_waitcnt vmcnt(26)
	ds_write2_b32 v109, v70, v71 offset1:1
	ds_write2_b32 v110, v72, v73 offset1:1
	s_waitcnt vmcnt(25)
	ds_write2_b32 v111, v74, v75 offset1:1
	ds_write2_b32 v112, v76, v77 offset1:1
	s_waitcnt vmcnt(24)
	ds_write2_b32 v113, v78, v79 offset1:1
	ds_write2_b32 v114, v80, v81 offset1:1
	s_waitcnt vmcnt(23)
	ds_write2_b32 v115, v82, v83 offset1:1
	ds_write2_b32 v116, v84, v85 offset1:1
	s_waitcnt vmcnt(22)
	ds_write2_b32 v117, v86, v87 offset1:1
	ds_write2_b32 v118, v88, v89 offset1:1
	s_waitcnt vmcnt(21)
	ds_write2_b32 v119, v94, v95 offset1:1
	ds_write2_b32 v120, v96, v97 offset1:1
	s_waitcnt vmcnt(20)
	ds_write2_b32 v121, v90, v91 offset1:1
	ds_write2_b32 v122, v92, v93 offset1:1
	s_and_b32 s1, s0, 0x7ffffe0
	s_waitcnt lgkmcnt(0)
	s_sub_i32 s19, s20, s1
	ds_read2_b32 v[70:71], v106 offset0:33 offset1:41
	ds_read2_b32 v[72:73], v106 offset1:8
	ds_read2_b32 v[74:75], v106 offset0:66 offset1:74
	ds_read2_b32 v[76:77], v106 offset0:99 offset1:107
	ds_read2_b32 v[78:79], v106 offset0:132 offset1:140
	ds_read2_b32 v[80:81], v106 offset0:165 offset1:173
	ds_read2_b32 v[82:83], v106 offset0:198 offset1:206
	ds_read2_b32 v[84:85], v106 offset0:231 offset1:239
	s_lshl_b32 s19, s19, 5
	s_lshl_b32 s0, s0, 1
	s_waitcnt lgkmcnt(6)
	v_cvt_pk_bf16_f32 v66, v72, v70
	v_or_b32_e32 v70, s19, v102
	s_andn2_b32 s0, s0, 63
	v_mul_lo_u32 v86, v70, s15
	s_ashr_i32 s1, s0, 31
	v_ashrrev_i32_e32 v87, 31, v86
	v_lshl_add_u64 v[86:87], s[78:79], 0, v[86:87]
	s_lshl_b64 s[0:1], s[0:1], 1
	v_lshl_add_u64 v[86:87], v[86:87], 0, s[0:1]
	v_mov_b32_e32 v101, v99
	v_or_b32_e32 v70, s19, v103
	s_waitcnt lgkmcnt(4)
	v_cvt_pk_bf16_f32 v67, v74, v76
	s_waitcnt lgkmcnt(2)
	v_cvt_pk_bf16_f32 v68, v78, v80
	s_waitcnt lgkmcnt(0)
	v_cvt_pk_bf16_f32 v69, v82, v84
	v_lshl_add_u64 v[86:87], v[86:87], 0, v[100:101]
	v_mul_lo_u32 v70, v70, s15
	global_store_dwordx4 v[86:87], v[66:69], off
	s_nop 1
	v_cvt_pk_bf16_f32 v66, v73, v71
	v_ashrrev_i32_e32 v71, 31, v70
	v_lshl_add_u64 v[70:71], s[78:79], 0, v[70:71]
	v_lshl_add_u64 v[70:71], v[70:71], 0, s[0:1]
	v_cvt_pk_bf16_f32 v67, v75, v77
	v_cvt_pk_bf16_f32 v68, v79, v81
	v_cvt_pk_bf16_f32 v69, v83, v85
	v_lshl_add_u64 v[70:71], v[70:71], 0, v[100:101]
	ds_read2_b32 v[72:73], v106 offset0:49 offset1:57
	ds_read2_b32 v[74:75], v106 offset0:16 offset1:24
	ds_read2_b32 v[76:77], v106 offset0:82 offset1:90
	ds_read2_b32 v[78:79], v106 offset0:115 offset1:123
	ds_read2_b32 v[80:81], v106 offset0:148 offset1:156
	ds_read2_b32 v[82:83], v106 offset0:181 offset1:189
	ds_read2_b32 v[84:85], v106 offset0:214 offset1:222
	ds_read2_b32 v[86:87], v106 offset0:247 offset1:255
	global_store_dwordx4 v[70:71], v[66:69], off
	v_or_b32_e32 v70, s19, v104
	v_mul_lo_u32 v70, v70, s15
	v_ashrrev_i32_e32 v71, 31, v70
	v_lshl_add_u64 v[70:71], s[78:79], 0, v[70:71]
	v_lshl_add_u64 v[70:71], v[70:71], 0, s[0:1]
	s_waitcnt lgkmcnt(6)
	v_cvt_pk_bf16_f32 v66, v74, v72
	s_waitcnt lgkmcnt(4)
	v_cvt_pk_bf16_f32 v67, v76, v78
	s_waitcnt lgkmcnt(2)
	v_cvt_pk_bf16_f32 v68, v80, v82
	s_waitcnt lgkmcnt(0)
	v_cvt_pk_bf16_f32 v69, v84, v86
	v_lshl_add_u64 v[70:71], v[70:71], 0, v[100:101]
	global_store_dwordx4 v[70:71], v[66:69], off
	v_or_b32_e32 v70, s19, v105
	v_mul_lo_u32 v70, v70, s15
	v_ashrrev_i32_e32 v71, 31, v70
	v_lshl_add_u64 v[70:71], s[78:79], 0, v[70:71]
	v_lshl_add_u64 v[70:71], v[70:71], 0, s[0:1]
	v_cvt_pk_bf16_f32 v66, v75, v73
	v_cvt_pk_bf16_f32 v67, v77, v79
	v_cvt_pk_bf16_f32 v68, v81, v83
	v_cvt_pk_bf16_f32 v69, v85, v87
	v_lshl_add_u64 v[70:71], v[70:71], 0, v[100:101]
	global_store_dwordx4 v[70:71], v[66:69], off
	s_waitcnt lgkmcnt(0)
	s_branch .LBB0_1692
.LBB0_1700:
	s_barrier
